# s29 + dma_saddr_p3: 7 more LDS-DMA loads (P3 K body) in the SGPR-base form, their 64-bit VALU address adds removed
# baseline (speedup 1.0000x reference)
.LBB0_425:
	s_add_u32 s12, s30, s38
	s_addc_u32 s42, s31, s39
	s_add_u32 s12, s12, 0xfff80080
	s_addc_u32 s65, s42, -1
	s_cmp_eq_u32 s64, 30
	s_cselect_b64 s[42:43], -1, 0
	s_and_b64 s[42:43], s[42:43], exec
	s_cselect_b32 s43, s19, s65
	s_cselect_b32 s42, s21, s12
	s_add_i32 s65, s64, 2
	s_cmp_eq_u32 s64, 30
	s_cselect_b64 s[66:67], -1, 0
	s_and_b64 s[68:69], s[66:67], exec
	s_cselect_b32 s12, 0, s65
	s_and_b64 s[66:67], s[66:67], s[4:5]
	s_and_b64 s[66:67], s[66:67], exec
	s_cselect_b32 s68, s23, s35
	s_cselect_b32 s69, s22, s34
	s_cselect_b32 s66, s27, s37
	s_cselect_b32 s67, s26, s36
	v_lshl_add_u64 v[214:215], s[44:45], 0, v[214:215]
	s_add_i32 m0, s29, 0xc000
	v_lshl_add_u64 v[2:3], s[44:45], 0, v[2:3]
	global_load_lds_dwordx4 v[214:215], off
	s_add_i32 m0, s29, 0xe000
	s_nop 0
	global_load_lds_dwordx4 v[2:3], off
	s_waitcnt vmcnt(8)
	s_waitcnt lgkmcnt(0)
	s_barrier
	s_setprio 1
	v_mfma_f32_16x16x32_bf16 v[128:131], v[148:151], v[188:191], v[128:131]
	v_mfma_f32_16x16x32_bf16 v[124:127], v[156:159], v[188:191], v[124:127]
	v_mfma_f32_16x16x32_bf16 v[112:115], v[148:151], v[180:183], v[112:115]
	v_mfma_f32_16x16x32_bf16 v[108:111], v[156:159], v[180:183], v[108:111]
	v_mfma_f32_16x16x32_bf16 v[96:99], v[148:151], v[172:175], v[96:99]
	v_mfma_f32_16x16x32_bf16 v[92:95], v[156:159], v[172:175], v[92:95]
	v_mfma_f32_16x16x32_bf16 v[80:83], v[148:151], v[164:167], v[80:83]
	v_mfma_f32_16x16x32_bf16 v[76:79], v[156:159], v[164:167], v[76:79]
	v_mfma_f32_16x16x32_bf16 v[128:131], v[152:155], v[192:195], v[128:131]
	v_mfma_f32_16x16x32_bf16 v[124:127], v[160:163], v[192:195], v[124:127]
	v_mfma_f32_16x16x32_bf16 v[112:115], v[152:155], v[184:187], v[112:115]
	v_mfma_f32_16x16x32_bf16 v[108:111], v[160:163], v[184:187], v[108:111]
	v_mfma_f32_16x16x32_bf16 v[96:99], v[152:155], v[176:179], v[96:99]
	v_mfma_f32_16x16x32_bf16 v[92:95], v[160:163], v[176:179], v[92:95]
	v_mfma_f32_16x16x32_bf16 v[80:83], v[152:155], v[168:171], v[80:83]
	v_mfma_f32_16x16x32_bf16 v[76:79], v[160:163], v[168:171], v[76:79]
	v_mfma_f32_16x16x32_bf16 v[120:123], v[132:135], v[188:191], v[120:123]
	v_mfma_f32_16x16x32_bf16 v[116:119], v[140:143], v[188:191], v[116:119]
	v_mfma_f32_16x16x32_bf16 v[104:107], v[132:135], v[180:183], v[104:107]
	v_mfma_f32_16x16x32_bf16 v[100:103], v[140:143], v[180:183], v[100:103]
	v_mfma_f32_16x16x32_bf16 v[88:91], v[132:135], v[172:175], v[88:91]
	v_mfma_f32_16x16x32_bf16 v[84:87], v[140:143], v[172:175], v[84:87]
	v_mfma_f32_16x16x32_bf16 v[72:75], v[132:135], v[164:167], v[72:75]
	v_mfma_f32_16x16x32_bf16 v[68:71], v[140:143], v[164:167], v[68:71]
	v_mfma_f32_16x16x32_bf16 v[120:123], v[136:139], v[192:195], v[120:123]
	v_mfma_f32_16x16x32_bf16 v[116:119], v[144:147], v[192:195], v[116:119]
	v_mfma_f32_16x16x32_bf16 v[104:107], v[136:139], v[184:187], v[104:107]
	v_mfma_f32_16x16x32_bf16 v[100:103], v[144:147], v[184:187], v[100:103]
	v_mfma_f32_16x16x32_bf16 v[88:91], v[136:139], v[176:179], v[88:91]
	v_mfma_f32_16x16x32_bf16 v[84:87], v[144:147], v[176:179], v[84:87]
	v_mfma_f32_16x16x32_bf16 v[72:75], v[136:139], v[168:171], v[72:75]
	v_mfma_f32_16x16x32_bf16 v[68:71], v[144:147], v[168:171], v[68:71]
	s_setprio 0
	s_barrier
	s_mov_b32 m0, s47
	v_lshl_add_u64 v[214:215], s[42:43], 0, v[198:199]
	s_add_u32 s44, s42, 0x80000
	ds_read_b128 v[164:167], v219 offset:16384
	ds_read_b128 v[168:171], v219 offset:17408
	ds_read_b128 v[172:175], v219 offset:18432
	ds_read_b128 v[176:179], v219 offset:19456
	ds_read_b128 v[180:183], v219 offset:20480
	ds_read_b128 v[184:187], v219 offset:21504
	ds_read_b128 v[188:191], v219 offset:22528
	ds_read_b128 v[192:195], v219 offset:23552
	global_load_lds_dwordx4 v[214:215], off
	v_lshl_add_u64 v[220:221], s[42:43], 0, v[202:203]
	s_mov_b32 m0, s48
	s_addc_u32 s45, s43, 0
	global_load_lds_dwordx4 v[220:221], off
	s_mov_b32 m0, s49
	s_add_i32 s70, s12, -8
	global_load_lds_dwordx4 v198, s[44:45]
	v_lshl_add_u64 v[2:3], s[44:45], 0, v[202:203]
	s_lshl_b64 s[44:45], s[12:13], 7
	s_add_u32 s71, s69, s44
	s_addc_u32 s72, s68, s45
	s_lshl_b32 s44, s70, 19
	s_add_u32 s73, s67, s44
	s_addc_u32 s74, s66, 0
	s_add_i32 s75, 0, 0x18000
	s_add_i32 s76, 0, 0x1c000
	s_add_u32 s77, s71, 0x80000
	s_addc_u32 s84, s72, 0
	s_add_u32 s85, s73, 0x800
	s_addc_u32 s86, s74, 0
	s_cmp_lt_u32 s70, 16
	s_cselect_b64 vcc, -1, 0
	s_and_b64 s[44:45], vcc, exec
	s_mov_b32 m0, s50
	v_cndmask_b32_e32 v222, v196, v204, vcc
	v_mov_b32_e32 v223, v1
	s_cselect_b32 s45, s74, s72
	s_cselect_b32 s44, s73, s71
	global_load_lds_dwordx4 v[2:3], off
	v_cndmask_b32_e32 v0, v200, v206, vcc
	s_mov_b32 m0, s29
	s_nop 0
	global_load_lds_dwordx4 v222, s[44:45]
	s_mov_b32 m0, s51
	s_nop 0
	global_load_lds_dwordx4 v0, s[44:45]
	s_waitcnt vmcnt(8)
	s_waitcnt lgkmcnt(0)
	s_barrier
	s_setprio 1
	v_mfma_f32_16x16x32_bf16 v[64:67], v[148:151], v[164:167], v[64:67]
	v_mfma_f32_16x16x32_bf16 v[60:63], v[156:159], v[164:167], v[60:63]
	v_mfma_f32_16x16x32_bf16 v[48:51], v[148:151], v[172:175], v[48:51]
	v_mfma_f32_16x16x32_bf16 v[44:47], v[156:159], v[172:175], v[44:47]
	v_mfma_f32_16x16x32_bf16 v[32:35], v[148:151], v[180:183], v[32:35]
	v_mfma_f32_16x16x32_bf16 v[28:31], v[156:159], v[180:183], v[28:31]
	v_mfma_f32_16x16x32_bf16 v[16:19], v[148:151], v[188:191], v[16:19]
	v_mfma_f32_16x16x32_bf16 v[12:15], v[156:159], v[188:191], v[12:15]
	v_mfma_f32_16x16x32_bf16 v[64:67], v[152:155], v[168:171], v[64:67]
	v_mfma_f32_16x16x32_bf16 v[60:63], v[160:163], v[168:171], v[60:63]
	v_mfma_f32_16x16x32_bf16 v[48:51], v[152:155], v[176:179], v[48:51]
	v_mfma_f32_16x16x32_bf16 v[44:47], v[160:163], v[176:179], v[44:47]
	v_mfma_f32_16x16x32_bf16 v[32:35], v[152:155], v[184:187], v[32:35]
	v_mfma_f32_16x16x32_bf16 v[28:31], v[160:163], v[184:187], v[28:31]
	v_mfma_f32_16x16x32_bf16 v[16:19], v[152:155], v[192:195], v[16:19]
	v_mfma_f32_16x16x32_bf16 v[12:15], v[160:163], v[192:195], v[12:15]
	v_mfma_f32_16x16x32_bf16 v[56:59], v[132:135], v[164:167], v[56:59]
	v_mfma_f32_16x16x32_bf16 v[52:55], v[140:143], v[164:167], v[52:55]
	v_mfma_f32_16x16x32_bf16 v[40:43], v[132:135], v[172:175], v[40:43]
	v_mfma_f32_16x16x32_bf16 v[36:39], v[140:143], v[172:175], v[36:39]
	v_mfma_f32_16x16x32_bf16 v[24:27], v[132:135], v[180:183], v[24:27]
	v_mfma_f32_16x16x32_bf16 v[20:23], v[140:143], v[180:183], v[20:23]
	v_mfma_f32_16x16x32_bf16 v[8:11], v[132:135], v[188:191], v[8:11]
	v_mfma_f32_16x16x32_bf16 v[2:5], v[140:143], v[188:191], v[4:7]
	v_mfma_f32_16x16x32_bf16 v[56:59], v[136:139], v[168:171], v[56:59]
	v_mfma_f32_16x16x32_bf16 v[52:55], v[144:147], v[168:171], v[52:55]
	v_mfma_f32_16x16x32_bf16 v[40:43], v[136:139], v[176:179], v[40:43]
	v_mfma_f32_16x16x32_bf16 v[36:39], v[144:147], v[176:179], v[36:39]
	v_mfma_f32_16x16x32_bf16 v[24:27], v[136:139], v[184:187], v[24:27]
	v_mfma_f32_16x16x32_bf16 v[20:23], v[144:147], v[184:187], v[20:23]
	v_mfma_f32_16x16x32_bf16 v[8:11], v[136:139], v[192:195], v[8:11]
	v_mfma_f32_16x16x32_bf16 v[2:5], v[144:147], v[192:195], v[2:5]
	s_setprio 0
	s_barrier
	v_add_u32_e32 v6, s75, v217
	ds_read_b128 v[148:151], v6
	ds_read_b128 v[152:155], v6 offset:1024
	ds_read_b128 v[156:159], v6 offset:2048
	ds_read_b128 v[160:163], v6 offset:3072
	v_add_u32_e32 v6, s76, v217
	ds_read_b128 v[132:135], v6
	ds_read_b128 v[136:139], v6 offset:1024
	ds_read_b128 v[140:143], v6 offset:2048
	ds_read_b128 v[144:147], v6 offset:3072
	s_cselect_b32 s45, s86, s84
	s_cselect_b32 s44, s85, s77
	s_mov_b32 m0, s52
	ds_read_b128 v[164:167], v219 offset:32768
	ds_read_b128 v[168:171], v219 offset:33792
	ds_read_b128 v[172:175], v219 offset:34816
	ds_read_b128 v[176:179], v219 offset:35840
	ds_read_b128 v[180:183], v219 offset:36864
	ds_read_b128 v[184:187], v219 offset:37888
	ds_read_b128 v[188:191], v219 offset:38912
	ds_read_b128 v[192:195], v219 offset:39936
	global_load_lds_dwordx4 v222, s[44:45]
	s_mov_b32 m0, s53
	s_nop 0
	global_load_lds_dwordx4 v0, s[44:45]
	s_waitcnt vmcnt(8)
	s_waitcnt lgkmcnt(0)
	s_barrier
	s_setprio 1
	v_mfma_f32_16x16x32_bf16 v[128:131], v[148:151], v[164:167], v[128:131]
	v_mfma_f32_16x16x32_bf16 v[124:127], v[156:159], v[164:167], v[124:127]
	v_mfma_f32_16x16x32_bf16 v[112:115], v[148:151], v[172:175], v[112:115]
	v_mfma_f32_16x16x32_bf16 v[108:111], v[156:159], v[172:175], v[108:111]
	v_mfma_f32_16x16x32_bf16 v[96:99], v[148:151], v[180:183], v[96:99]
	v_mfma_f32_16x16x32_bf16 v[92:95], v[156:159], v[180:183], v[92:95]
	v_mfma_f32_16x16x32_bf16 v[80:83], v[148:151], v[188:191], v[80:83]
	v_mfma_f32_16x16x32_bf16 v[76:79], v[156:159], v[188:191], v[76:79]
	v_mfma_f32_16x16x32_bf16 v[128:131], v[152:155], v[168:171], v[128:131]
	v_mfma_f32_16x16x32_bf16 v[124:127], v[160:163], v[168:171], v[124:127]
	v_mfma_f32_16x16x32_bf16 v[112:115], v[152:155], v[176:179], v[112:115]
	v_mfma_f32_16x16x32_bf16 v[108:111], v[160:163], v[176:179], v[108:111]
	v_mfma_f32_16x16x32_bf16 v[96:99], v[152:155], v[184:187], v[96:99]
	v_mfma_f32_16x16x32_bf16 v[92:95], v[160:163], v[184:187], v[92:95]
	v_mfma_f32_16x16x32_bf16 v[80:83], v[152:155], v[192:195], v[80:83]
	v_mfma_f32_16x16x32_bf16 v[76:79], v[160:163], v[192:195], v[76:79]
	v_mfma_f32_16x16x32_bf16 v[120:123], v[132:135], v[164:167], v[120:123]
	v_mfma_f32_16x16x32_bf16 v[116:119], v[140:143], v[164:167], v[116:119]
	v_mfma_f32_16x16x32_bf16 v[104:107], v[132:135], v[172:175], v[104:107]
	v_mfma_f32_16x16x32_bf16 v[100:103], v[140:143], v[172:175], v[100:103]
	v_mfma_f32_16x16x32_bf16 v[88:91], v[132:135], v[180:183], v[88:91]
	v_mfma_f32_16x16x32_bf16 v[84:87], v[140:143], v[180:183], v[84:87]
	v_mfma_f32_16x16x32_bf16 v[72:75], v[132:135], v[188:191], v[72:75]
	v_mfma_f32_16x16x32_bf16 v[68:71], v[140:143], v[188:191], v[68:71]
	v_mfma_f32_16x16x32_bf16 v[120:123], v[136:139], v[168:171], v[120:123]
	v_mfma_f32_16x16x32_bf16 v[116:119], v[144:147], v[168:171], v[116:119]
	v_mfma_f32_16x16x32_bf16 v[104:107], v[136:139], v[176:179], v[104:107]
	v_mfma_f32_16x16x32_bf16 v[100:103], v[144:147], v[176:179], v[100:103]
	v_mfma_f32_16x16x32_bf16 v[88:91], v[136:139], v[184:187], v[88:91]
	v_mfma_f32_16x16x32_bf16 v[84:87], v[144:147], v[184:187], v[84:87]
	v_mfma_f32_16x16x32_bf16 v[72:75], v[136:139], v[192:195], v[72:75]
	v_mfma_f32_16x16x32_bf16 v[68:71], v[144:147], v[192:195], v[68:71]
	s_setprio 0
	s_barrier
	s_add_i32 s44, s75, s33
	v_lshl_add_u64 v[6:7], v[214:215], 0, s[14:15]
	s_mov_b32 m0, s44
	ds_read_b128 v[188:191], v219 offset:49152
	ds_read_b128 v[192:195], v219 offset:50176
	ds_read_b128 v[180:183], v219 offset:51200
	ds_read_b128 v[184:187], v219 offset:52224
	ds_read_b128 v[172:175], v219 offset:53248
	ds_read_b128 v[176:179], v219 offset:54272
	ds_read_b128 v[164:167], v219 offset:55296
	ds_read_b128 v[168:171], v219 offset:56320
	global_load_lds_dwordx4 v[6:7], off
	s_add_i32 m0, s44, 0x2000
	s_add_u32 s42, s42, 0x80080
	v_lshl_add_u64 v[6:7], v[220:221], 0, s[14:15]
	s_addc_u32 s43, s43, 0
	s_add_i32 s44, s76, s33
	global_load_lds_dwordx4 v[6:7], off
	s_mov_b32 m0, s44
	s_add_i32 s70, s12, -7
	global_load_lds_dwordx4 v198, s[42:43]
	s_add_i32 m0, s44, 0x2000
	s_cmp_gt_u32 s70, 15
	global_load_lds_dwordx4 v202, s[42:43]
	s_mov_b64 s[44:45], -1
	s_cbranch_scc0 .LBB0_427
	s_or_b32 s12, s12, 1
	s_lshl_b64 s[42:43], s[12:13], 7
	s_add_u32 s42, s69, s42
	s_addc_u32 s43, s68, s43
	s_mov_b64 s[44:45], 0
